# MLA softmax VALU trims: removed inline-asm pad nops and self-max canonicalisation in the max chain, skip dead -1e30 score initialisation when both key halves are attended, folded +0 row-sum inits and
# speedup vs baseline: 1.0777x; 1.0082x over previous
; template <int DQK>
; __device__ __forceinline__ void attn_block(const AttnKV& a, const AttnW& gw, char* smem) {
;     ...
;             __builtin_amdgcn_s_setprio(1);
; #pragma unroll
;             for (int nt = 0; nt < 8; ++nt) {
;                 if (nt < 4 || hc >= 2) {
;                     st[0][nt] = (f32x4){0.f, 0.f, 0.f, 0.f}; st[1][nt] = (f32x4){0.f, 0.f, 0.f, 0.f};
; #pragma unroll
;                     for (int ks = 0; ks < KS; ++ks) {
;                         const bf16x8 kf = *(const bf16x8*)(Ks + (nt * 16 + lr) * KROWB + (ks * 4 + lq) * 16);
;                         st[0][nt] = __builtin_amdgcn_mfma_f32_16x16x32_bf16(kf, qf[0][ks], st[0][nt], 0, 0, 0);
;                         st[1][nt] = __builtin_amdgcn_mfma_f32_16x16x32_bf16(kf, qf[1][ks], st[1][nt], 0, 0, 0);
;                     }
;                 } else {
;                     st[0][nt] = (f32x4){-1e30f, -1e30f, -1e30f, -1e30f}; st[1][nt] = st[0][nt];
;                 }
;             }
;             __builtin_amdgcn_s_setprio(0);
.LBB0_1715:
	s_bitcmp1_b32 s8, 0
	s_cselect_b32 s21, 0xb400, 0
	s_setprio 1
	v_add_u32_e32 v82, s21, v155
	v_add_u32_e32 v149, v82, v146
	ds_read_b128 v[194:197], v149
	ds_read_b128 v[198:201], v149 offset:64
	ds_read_b128 v[202:205], v149 offset:128
	ds_read_b128 v[206:209], v149 offset:3584
	ds_read_b128 v[210:213], v149 offset:3648
	ds_read_b128 v[214:217], v149 offset:3712
	ds_read_b128 v[218:221], v149 offset:7168
	ds_read_b128 v[222:225], v149 offset:7232
	ds_read_b128 v[226:229], v149 offset:7296
	ds_read_b128 v[230:233], v149 offset:10752
	v_cmp_ne_u32_e64 s[8:9], 1, v3
	s_waitcnt lgkmcnt(7)
	v_mfma_f32_16x16x32_bf16 v[114:117], v[194:197], v[6:9], 0
	v_mfma_f32_16x16x32_bf16 v[82:85], v[194:197], v[18:21], 0
	v_mfma_f32_16x16x32_bf16 v[114:117], v[198:201], v[10:13], v[114:117]
	v_mfma_f32_16x16x32_bf16 v[82:85], v[198:201], v[22:25], v[82:85]
	v_mfma_f32_16x16x32_bf16 v[114:117], v[202:205], v[14:17], v[114:117]
	v_mfma_f32_16x16x32_bf16 v[82:85], v[202:205], v[26:29], v[82:85]
	ds_read_b128 v[194:197], v149 offset:10816
	ds_read_b128 v[198:201], v149 offset:10880
	s_waitcnt lgkmcnt(6)
	v_mfma_f32_16x16x32_bf16 v[118:121], v[206:209], v[6:9], 0
	v_mfma_f32_16x16x32_bf16 v[86:89], v[206:209], v[18:21], 0
	v_mfma_f32_16x16x32_bf16 v[118:121], v[210:213], v[10:13], v[118:121]
	v_mfma_f32_16x16x32_bf16 v[86:89], v[210:213], v[22:25], v[86:89]
	v_mfma_f32_16x16x32_bf16 v[118:121], v[214:217], v[14:17], v[118:121]
	v_mfma_f32_16x16x32_bf16 v[86:89], v[214:217], v[26:29], v[86:89]
	s_waitcnt lgkmcnt(3)
	v_mfma_f32_16x16x32_bf16 v[122:125], v[218:221], v[6:9], 0
	v_mfma_f32_16x16x32_bf16 v[90:93], v[218:221], v[18:21], 0
	v_mfma_f32_16x16x32_bf16 v[122:125], v[222:225], v[10:13], v[122:125]
	v_mfma_f32_16x16x32_bf16 v[90:93], v[222:225], v[22:25], v[90:93]
	v_mfma_f32_16x16x32_bf16 v[122:125], v[226:229], v[14:17], v[122:125]
	v_mfma_f32_16x16x32_bf16 v[90:93], v[226:229], v[26:29], v[90:93]
	s_waitcnt lgkmcnt(0)
	v_mfma_f32_16x16x32_bf16 v[126:129], v[230:233], v[6:9], 0
	v_mfma_f32_16x16x32_bf16 v[98:101], v[230:233], v[18:21], 0
	v_mfma_f32_16x16x32_bf16 v[126:129], v[194:197], v[10:13], v[126:129]
	v_mfma_f32_16x16x32_bf16 v[98:101], v[194:197], v[22:25], v[98:101]
	v_mfma_f32_16x16x32_bf16 v[126:129], v[198:201], v[14:17], v[126:129]
	v_mfma_f32_16x16x32_bf16 v[98:101], v[198:201], v[26:29], v[98:101]
	s_cmp_lg_u64 s[8:9], 0
	s_cbranch_scc1 .Lmy_skipinit_1716
	v_mov_b32_e32 v130, 0xf149f2ca
	v_mov_b32_e32 v131, 0xf149f2ca
	v_mov_b32_e32 v132, 0xf149f2ca
	v_mov_b32_e32 v133, 0xf149f2ca
	v_mov_b32_e32 v102, 0xf149f2ca
	v_mov_b32_e32 v103, 0xf149f2ca
	v_mov_b32_e32 v104, 0xf149f2ca
	s_nop 0
	v_mov_b32_e32 v94, 0xf149f2ca
	v_mov_b32_e32 v105, 0xf149f2ca
.Lmy_skipinit_1716:
	s_and_saveexec_b64 s[16:17], s[8:9]
	s_cbranch_execz .LBB0_1717
	ds_read_b128 v[102:105], v149 offset:14336
	ds_read_b128 v[106:109], v149 offset:14400
	s_waitcnt lgkmcnt(0)
	v_mfma_f32_16x16x32_bf16 v[110:113], v[102:105], v[6:9], 0
	v_mfma_f32_16x16x32_bf16 v[102:105], v[102:105], v[18:21], 0
	v_mfma_f32_16x16x32_bf16 v[110:113], v[106:109], v[10:13], v[110:113]
	v_mfma_f32_16x16x32_bf16 v[102:105], v[106:109], v[22:25], v[102:105]
	ds_read_b128 v[106:109], v149 offset:14464
	s_waitcnt lgkmcnt(0)
	v_mfma_f32_16x16x32_bf16 v[130:133], v[106:109], v[14:17], v[110:113]
	v_mfma_f32_16x16x32_bf16 v[102:105], v[106:109], v[26:29], v[102:105]
.LBB0_1717:
	s_or_b64 exec, exec, s[16:17]
	s_cmp_lg_u64 s[8:9], 0
	s_cbranch_scc1 .Lmy_skipinit_1717
	v_mov_b32_e32 v95, 0xf149f2ca
	v_mov_b32_e32 v96, 0xf149f2ca
	v_mov_b32_e32 v97, 0xf149f2ca
	v_mov_b32_e32 v134, 0xf149f2ca
	v_mov_b32_e32 v135, 0xf149f2ca
	v_mov_b32_e32 v136, 0xf149f2ca
	v_mov_b32_e32 v137, 0xf149f2ca
.Lmy_skipinit_1717:
	s_and_saveexec_b64 s[16:17], s[8:9]
	s_cbranch_execz .LBB0_1719
	ds_read_b128 v[94:97], v149 offset:17920
	ds_read_b128 v[106:109], v149 offset:17984
	s_waitcnt lgkmcnt(0)
	v_mfma_f32_16x16x32_bf16 v[110:113], v[94:97], v[6:9], 0
	v_mfma_f32_16x16x32_bf16 v[94:97], v[94:97], v[18:21], 0
	v_mfma_f32_16x16x32_bf16 v[110:113], v[106:109], v[10:13], v[110:113]
	v_mfma_f32_16x16x32_bf16 v[94:97], v[106:109], v[22:25], v[94:97]
	ds_read_b128 v[106:109], v149 offset:18048
	s_waitcnt lgkmcnt(0)
	v_mfma_f32_16x16x32_bf16 v[134:137], v[106:109], v[14:17], v[110:113]
	v_mfma_f32_16x16x32_bf16 v[94:97], v[106:109], v[26:29], v[94:97]
.LBB0_1719:
	s_or_b64 exec, exec, s[16:17]
	s_cmp_lg_u64 s[8:9], 0
	s_cbranch_scc1 .Lmy_skipinit_1719
	v_mov_b32_e32 v106, 0xf149f2ca
	s_nop 0
	v_mov_b32_e32 v110, 0xf149f2ca
	v_mov_b32_e32 v111, 0xf149f2ca
	v_mov_b32_e32 v112, 0xf149f2ca
	v_mov_b32_e32 v113, 0xf149f2ca
	v_mov_b32_e32 v138, 0xf149f2ca
	v_mov_b32_e32 v139, 0xf149f2ca
	v_mov_b32_e32 v140, 0xf149f2ca
	v_mov_b32_e32 v141, 0xf149f2ca
.Lmy_skipinit_1719:
	s_and_saveexec_b64 s[16:17], s[8:9]
	s_cbranch_execz .LBB0_1721
	ds_read_b128 v[108:111], v149 offset:21504
	ds_read_b128 v[138:141], v149 offset:21568
	ds_read_b128 v[170:173], v149 offset:21632
	s_waitcnt lgkmcnt(0)
	v_mfma_f32_16x16x32_bf16 v[142:145], v[108:111], v[6:9], 0
	v_mfma_f32_16x16x32_bf16 v[108:111], v[108:111], v[18:21], 0
	v_mfma_f32_16x16x32_bf16 v[142:145], v[138:141], v[10:13], v[142:145]
	v_mfma_f32_16x16x32_bf16 v[108:111], v[138:141], v[22:25], v[108:111]
	v_mfma_f32_16x16x32_bf16 v[138:141], v[170:173], v[14:17], v[142:145]
	v_mfma_f32_16x16x32_bf16 v[110:113], v[170:173], v[26:29], v[108:111]
.LBB0_1721:
	s_or_b64 exec, exec, s[16:17]
	s_cmp_lg_u64 s[8:9], 0
	s_cbranch_scc1 .Lmy_skipinit_1721
	v_mov_b32_e32 v107, 0xf149f2ca
	s_nop 3
	v_mov_b32_e32 v108, 0xf149f2ca
	v_mov_b32_e32 v109, 0xf149f2ca
	v_mov_b32_e32 v142, 0xf149f2ca
	v_mov_b32_e32 v143, 0xf149f2ca
	v_mov_b32_e32 v144, 0xf149f2ca
	v_mov_b32_e32 v145, 0xf149f2ca
; template <int DQK>
; __device__ __forceinline__ void attn_block(const AttnKV& a, const AttnW& gw, char* smem) {
;     ...
;                     for (int ks = 0; ks < KS; ++ks) {
;                         const bf16x8 kf = *(const bf16x8*)(Ks + (nt * 16 + lr) * KROWB + (ks * 4 + lq) * 16);
;                         st[0][nt] = __builtin_amdgcn_mfma_f32_16x16x32_bf16(kf, qf[0][ks], st[0][nt], 0, 0, 0);
;                         st[1][nt] = __builtin_amdgcn_mfma_f32_16x16x32_bf16(kf, qf[1][ks], st[1][nt], 0, 0, 0);
;                     }
;                 } else {
;                     st[0][nt] = (f32x4){-1e30f, -1e30f, -1e30f, -1e30f}; st[1][nt] = st[0][nt];
;                 }
;             }
;             __builtin_amdgcn_s_setprio(0);
; #pragma unroll
;             for (int qt = 0; qt < 2; ++qt) {
;                 if (slope2 != 0.f) {
;                     const int qd = wh * 32 + qt * 16 + lr + dist0 - kt * 128 - lq * 4;
; #pragma unroll
;                     for (int nt = 0; nt < 8; ++nt)
; #pragma unroll
;                         for (int jj = 0; jj < 4; ++jj) st[qt][nt][jj] -= slope2 * fabsf((float)(qd - nt * 16 - jj));
;                 }
;                 float mxa = max3f(st[qt][0][0], st[qt][0][1], st[qt][0][2]), mxb = max3f(st[qt][0][3], st[qt][1][0], st[qt][1][1]);
;                 mxa = max3f(mxa, st[qt][1][2], st[qt][1][3]);
; #pragma unroll
;                 for (int nt = 2; nt < 8; nt += 2) {
;                     mxb = max3f(mxb, st[qt][nt][0], st[qt][nt][1]); mxa = max3f(mxa, st[qt][nt][2], st[qt][nt][3]);
;                     mxb = max3f(mxb, st[qt][nt + 1][0], st[qt][nt + 1][1]); mxa = max3f(mxa, st[qt][nt + 1][2], st[qt][nt + 1][3]);
;                 }
;                 float mx = fmaxf(mxa, mxb);
;                 mx = fmaxf(mx, __shfl_xor(mx, 16)); mx = fmaxf(mx, __shfl_xor(mx, 32));
;                 const float mnew = fmaxf(m[qt], mx);
;                 const float alpha = __builtin_amdgcn_exp2f(m[qt] - mnew);
;                 m[qt] = mnew;
;                 f32x4 rs4 = {0.f, 0.f, 0.f, 0.f};
;                 const f32x4 negm4 = {-mnew, -mnew, -mnew, -mnew};
; #pragma unroll
;                 for (int nt = 0; nt < 8; ++nt) {
;                     const f32x4 d4 = st[qt][nt] + negm4;
;                     f32x4 e4;
.Lmy_skipinit_1721:
	s_and_saveexec_b64 s[16:17], s[8:9]
	s_cbranch_execz .LBB0_1723
	ds_read_b128 v[106:109], v149 offset:25088
	ds_read_b128 v[142:145], v149 offset:25152
	ds_read_b128 v[174:177], v149 offset:25216
	s_waitcnt lgkmcnt(0)
	v_mfma_f32_16x16x32_bf16 v[170:173], v[106:109], v[6:9], 0
	v_mfma_f32_16x16x32_bf16 v[106:109], v[106:109], v[18:21], 0
	v_mfma_f32_16x16x32_bf16 v[170:173], v[142:145], v[10:13], v[170:173]
	v_mfma_f32_16x16x32_bf16 v[106:109], v[142:145], v[22:25], v[106:109]
	v_mfma_f32_16x16x32_bf16 v[142:145], v[174:177], v[14:17], v[170:173]
	v_mfma_f32_16x16x32_bf16 v[106:109], v[174:177], v[26:29], v[106:109]
.LBB0_1723:
	s_or_b64 exec, exec, s[16:17]
	s_setprio 0
	v_max3_f32 v149, v114, v115, v116
	v_max3_f32 v151, v117, v118, v119
	v_max3_f32 v149, v149, v120, v121
	v_max3_f32 v151, v151, v122, v123
	v_max3_f32 v149, v149, v124, v125
	v_max3_f32 v151, v151, v126, v127
	v_max3_f32 v149, v149, v128, v129
	v_max3_f32 v151, v151, v130, v131
	v_max3_f32 v149, v149, v132, v133
	v_max3_f32 v151, v151, v134, v135
	v_max3_f32 v149, v149, v136, v137
	v_max3_f32 v151, v151, v138, v139
	v_max3_f32 v149, v149, v140, v141
	v_max3_f32 v151, v151, v142, v143
	v_max3_f32 v149, v149, v144, v145
	v_max_f32_e32 v151, v149, v151
	v_mov_b32_e32 v170, v151
	s_nop 1
	v_permlane16_swap_b32 v151, v170
	v_max_f32_e32 v170, v151, v170
	v_mov_b32_e32 v151, v170
	s_nop 1
	v_permlane32_swap_b32 v170, v151
	v_max3_f32 v168, v186, v170, v151
	v_pk_add_f32 v[116:117], v[116:117], v[168:169] op_sel_hi:[1,0] neg_lo:[0,1] neg_hi:[0,1]
	v_pk_add_f32 v[114:115], v[114:115], v[168:169] op_sel_hi:[1,0] neg_lo:[0,1] neg_hi:[0,1]
	v_exp_f32_e32 v180, v116
	v_exp_f32_e32 v178, v114
	v_exp_f32_e32 v179, v115
	v_exp_f32_e32 v181, v117
	v_pk_add_f32 v[114:115], v[120:121], v[168:169] op_sel_hi:[1,0] neg_lo:[0,1] neg_hi:[0,1]
	v_pk_add_f32 v[116:117], v[118:119], v[168:169] op_sel_hi:[1,0] neg_lo:[0,1] neg_hi:[0,1]
	v_exp_f32_e32 v184, v114
	v_exp_f32_e32 v182, v116
	v_exp_f32_e32 v185, v115
	v_exp_f32_e32 v183, v117
	v_pk_add_f32 v[118:119], v[124:125], v[168:169] op_sel_hi:[1,0] neg_lo:[0,1] neg_hi:[0,1]
	v_pk_add_f32 v[120:121], v[122:123], v[168:169] op_sel_hi:[1,0] neg_lo:[0,1] neg_hi:[0,1]
	v_exp_f32_e32 v172, v118
	v_exp_f32_e32 v170, v120
	v_exp_f32_e32 v171, v121
	v_exp_f32_e32 v173, v119
	v_pk_add_f32 v[118:119], v[128:129], v[168:169] op_sel_hi:[1,0] neg_lo:[0,1] neg_hi:[0,1]
	v_pk_add_f32 v[120:121], v[126:127], v[168:169] op_sel_hi:[1,0] neg_lo:[0,1] neg_hi:[0,1]
	v_exp_f32_e32 v176, v118
	v_exp_f32_e32 v174, v120
	v_exp_f32_e32 v177, v119
	v_exp_f32_e32 v175, v121
	v_pk_add_f32 v[118:119], v[132:133], v[168:169] op_sel_hi:[1,0] neg_lo:[0,1] neg_hi:[0,1]
	v_pk_add_f32 v[120:121], v[130:131], v[168:169] op_sel_hi:[1,0] neg_lo:[0,1] neg_hi:[0,1]
	v_exp_f32_e32 v126, v120
	v_exp_f32_e32 v127, v121
	v_exp_f32_e32 v128, v118
	v_exp_f32_e32 v129, v119
	v_pk_add_f32 v[118:119], v[136:137], v[168:169] op_sel_hi:[1,0] neg_lo:[0,1] neg_hi:[0,1]
	v_pk_add_f32 v[120:121], v[134:135], v[168:169] op_sel_hi:[1,0] neg_lo:[0,1] neg_hi:[0,1]
	v_pk_add_f32 v[116:117], v[184:185], v[180:181]
	v_pk_add_f32 v[114:115], v[182:183], v[178:179]
	v_exp_f32_e32 v130, v120
	v_exp_f32_e32 v132, v118
	v_exp_f32_e32 v133, v119
	v_exp_f32_e32 v131, v121
	v_pk_add_f32 v[120:121], v[140:141], v[168:169] op_sel_hi:[1,0] neg_lo:[0,1] neg_hi:[0,1]
	v_pk_add_f32 v[118:119], v[138:139], v[168:169] op_sel_hi:[1,0] neg_lo:[0,1] neg_hi:[0,1]
	v_pk_add_f32 v[114:115], v[170:171], v[114:115]
	v_pk_add_f32 v[116:117], v[172:173], v[116:117]
	v_exp_f32_e32 v118, v118
	v_exp_f32_e32 v119, v119
	v_exp_f32_e32 v120, v120
	v_exp_f32_e32 v121, v121
	v_pk_add_f32 v[124:125], v[144:145], v[168:169] op_sel_hi:[1,0] neg_lo:[0,1] neg_hi:[0,1]
	v_pk_add_f32 v[122:123], v[142:143], v[168:169] op_sel_hi:[1,0] neg_lo:[0,1] neg_hi:[0,1]
	v_pk_add_f32 v[116:117], v[176:177], v[116:117]
	v_pk_add_f32 v[114:115], v[174:175], v[114:115]
	v_exp_f32_e32 v122, v122
	v_exp_f32_e32 v124, v124
	v_exp_f32_e32 v125, v125
	v_exp_f32_e32 v123, v123
	v_pk_add_f32 v[114:115], v[126:127], v[114:115]
	v_pk_add_f32 v[116:117], v[128:129], v[116:117]
	v_pk_add_f32 v[114:115], v[130:131], v[114:115]
	v_pk_add_f32 v[116:117], v[132:133], v[116:117]
	v_pk_add_f32 v[114:115], v[118:119], v[114:115]
	v_pk_add_f32 v[116:117], v[120:121], v[116:117]
	v_pk_add_f32 v[114:115], v[122:123], v[114:115]
	v_pk_add_f32 v[116:117], v[124:125], v[116:117]
	v_add_f32_e32 v114, v114, v115
	v_add_f32_e32 v115, v116, v117
	v_add_f32_e32 v115, v114, v115
	v_mov_b32_e32 v116, v115
	v_sub_f32_e32 v114, v186, v168
	v_exp_f32_e32 v114, v114
	v_permlane16_swap_b32 v115, v116
	v_add_f32_e32 v115, v115, v116
	v_mov_b32_e32 v117, v115
	s_nop 1
	v_permlane32_swap_b32 v115, v117
	v_cmp_neq_f32_e32 vcc, 1.0, v114
	s_cbranch_vccz .LBB0_1725
	v_pk_mul_f32 v[80:81], v[80:81], v[114:115] op_sel_hi:[1,0]
	v_pk_mul_f32 v[78:79], v[78:79], v[114:115] op_sel_hi:[1,0]
	v_pk_mul_f32 v[76:77], v[76:77], v[114:115] op_sel_hi:[1,0]
	v_pk_mul_f32 v[74:75], v[74:75], v[114:115] op_sel_hi:[1,0]
	v_pk_mul_f32 v[72:73], v[72:73], v[114:115] op_sel_hi:[1,0]
	v_pk_mul_f32 v[70:71], v[70:71], v[114:115] op_sel_hi:[1,0]
	v_pk_mul_f32 v[68:69], v[68:69], v[114:115] op_sel_hi:[1,0]
	v_pk_mul_f32 v[66:67], v[66:67], v[114:115] op_sel_hi:[1,0]
; __device__ __forceinline__ float max3f(float a, float b, float c) { float r; asm("v_max3_f32 %0, %1, %2, %3" : "=v"(r) : "v"(a), "v"(b), "v"(c)); return r; }
; template <int DQK>
; __device__ __forceinline__ void attn_block(const AttnKV& a, const AttnW& gw, char* smem) {
;     ...
;                 float mxa = max3f(st[qt][0][0], st[qt][0][1], st[qt][0][2]), mxb = max3f(st[qt][0][3], st[qt][1][0], st[qt][1][1]);
;                 mxa = max3f(mxa, st[qt][1][2], st[qt][1][3]);
; #pragma unroll
;                 for (int nt = 2; nt < 8; nt += 2) {
;                     mxb = max3f(mxb, st[qt][nt][0], st[qt][nt][1]); mxa = max3f(mxa, st[qt][nt][2], st[qt][nt][3]);
;                     mxb = max3f(mxb, st[qt][nt + 1][0], st[qt][nt + 1][1]); mxa = max3f(mxa, st[qt][nt + 1][2], st[qt][nt + 1][3]);
;                 }
;                 float mx = fmaxf(mxa, mxb);
;                 mx = fmaxf(mx, __shfl_xor(mx, 16)); mx = fmaxf(mx, __shfl_xor(mx, 32));
;                 const float mnew = fmaxf(m[qt], mx);
;                 const float alpha = __builtin_amdgcn_exp2f(m[qt] - mnew);
;                 m[qt] = mnew;
;                 f32x4 rs4 = {0.f, 0.f, 0.f, 0.f};
;                 const f32x4 negm4 = {-mnew, -mnew, -mnew, -mnew};
; #pragma unroll
;                 for (int nt = 0; nt < 8; ++nt) {
;                     const f32x4 d4 = st[qt][nt] + negm4;
;                     f32x4 e4;
;                     e4[0] = __builtin_amdgcn_exp2f(d4[0]); e4[1] = __builtin_amdgcn_exp2f(d4[1]); e4[2] = __builtin_amdgcn_exp2f(d4[2]); e4[3] = __builtin_amdgcn_exp2f(d4[3]);
;                     st[qt][nt] = e4; rs4 += e4;
;                 }
;                 float rs = (rs4[0] + rs4[1]) + (rs4[2] + rs4[3]);
;                 rs += __shfl_xor(rs, 16); rs += __shfl_xor(rs, 32);
;                 l[qt] = l[qt] * alpha + rs;
;                 if (__builtin_amdgcn_ballot_w64(alpha != 1.0f) != 0ull) {
; #pragma unroll
;                     for (int dt = 0; dt < 4; ++dt) ot[qt][dt] *= alpha;
;                 }
.LBB0_1725:
	v_max3_f32 v116, v82, v83, v84
	v_max3_f32 v134, v85, v86, v87
	v_max3_f32 v116, v116, v88, v89
	v_max3_f32 v134, v134, v90, v91
	v_max3_f32 v116, v116, v92, v93
	v_max3_f32 v134, v134, v98, v99
	v_max3_f32 v116, v116, v100, v101
	v_max3_f32 v134, v134, v102, v103
	v_max3_f32 v116, v116, v104, v105
	v_max3_f32 v134, v134, v94, v95
	v_max3_f32 v116, v116, v96, v97
	v_max3_f32 v134, v134, v110, v111
	v_max3_f32 v116, v116, v112, v113
	v_max3_f32 v134, v134, v106, v107
	v_max3_f32 v116, v116, v108, v109
	v_max_f32_e32 v116, v116, v134
	v_mov_b32_e32 v134, v116
	s_nop 1
	v_permlane16_swap_b32 v116, v134
	v_max_f32_e32 v116, v116, v134
	v_mov_b32_e32 v134, v116
	s_nop 1
	v_permlane32_swap_b32 v116, v134
	v_max3_f32 v116, v193, v116, v134
	v_pk_add_f32 v[84:85], v[84:85], v[116:117] op_sel_hi:[1,0] neg_lo:[0,1] neg_hi:[0,1]
	v_pk_add_f32 v[82:83], v[82:83], v[116:117] op_sel_hi:[1,0] neg_lo:[0,1] neg_hi:[0,1]
	v_exp_f32_e32 v142, v84
	v_exp_f32_e32 v140, v82
	v_exp_f32_e32 v141, v83
	v_exp_f32_e32 v143, v85
	v_pk_add_f32 v[82:83], v[88:89], v[116:117] op_sel_hi:[1,0] neg_lo:[0,1] neg_hi:[0,1]
	v_pk_add_f32 v[84:85], v[86:87], v[116:117] op_sel_hi:[1,0] neg_lo:[0,1] neg_hi:[0,1]
	v_exp_f32_e32 v186, v82
	v_exp_f32_e32 v187, v83
	v_pk_add_f32 v[86:87], v[92:93], v[116:117] op_sel_hi:[1,0] neg_lo:[0,1] neg_hi:[0,1]
	v_pk_add_f32 v[88:89], v[90:91], v[116:117] op_sel_hi:[1,0] neg_lo:[0,1] neg_hi:[0,1]
	v_exp_f32_e32 v136, v86
	v_exp_f32_e32 v137, v87
	v_pk_add_f32 v[86:87], v[100:101], v[116:117] op_sel_hi:[1,0] neg_lo:[0,1] neg_hi:[0,1]
	v_exp_f32_e32 v144, v84
	v_exp_f32_e32 v138, v86
	v_exp_f32_e32 v139, v87
	v_pk_add_f32 v[86:87], v[104:105], v[116:117] op_sel_hi:[1,0] neg_lo:[0,1] neg_hi:[0,1]
	v_exp_f32_e32 v145, v85
	v_exp_f32_e32 v134, v88
	v_exp_f32_e32 v135, v89
	v_pk_add_f32 v[88:89], v[98:99], v[116:117] op_sel_hi:[1,0] neg_lo:[0,1] neg_hi:[0,1]
	v_exp_f32_e32 v98, v86
	v_exp_f32_e32 v99, v87
	v_pk_add_f32 v[86:87], v[96:97], v[116:117] op_sel_hi:[1,0] neg_lo:[0,1] neg_hi:[0,1]
	v_pk_add_f32 v[84:85], v[186:187], v[142:143]
	v_exp_f32_e32 v96, v86
	v_exp_f32_e32 v97, v87
	v_pk_add_f32 v[84:85], v[136:137], v[84:85]
	v_exp_f32_e32 v100, v88
	v_exp_f32_e32 v101, v89
	v_pk_add_f32 v[84:85], v[138:139], v[84:85]
	v_pk_add_f32 v[88:89], v[102:103], v[116:117] op_sel_hi:[1,0] neg_lo:[0,1] neg_hi:[0,1]
	v_exp_f32_e32 v92, v88
	v_exp_f32_e32 v93, v89
	v_pk_add_f32 v[88:89], v[94:95], v[116:117] op_sel_hi:[1,0] neg_lo:[0,1] neg_hi:[0,1]
	v_pk_add_f32 v[84:85], v[98:99], v[84:85]
	v_pk_add_f32 v[82:83], v[144:145], v[140:141]
	v_exp_f32_e32 v94, v88
	v_exp_f32_e32 v95, v89
	v_pk_add_f32 v[102:103], v[96:97], v[84:85]
	v_pk_add_f32 v[86:87], v[112:113], v[116:117] op_sel_hi:[1,0] neg_lo:[0,1] neg_hi:[0,1]
	v_pk_add_f32 v[84:85], v[110:111], v[116:117] op_sel_hi:[1,0] neg_lo:[0,1] neg_hi:[0,1]
	v_pk_add_f32 v[82:83], v[134:135], v[82:83]
	v_exp_f32_e32 v84, v84
	v_exp_f32_e32 v85, v85
	v_exp_f32_e32 v86, v86
	v_exp_f32_e32 v87, v87
	v_pk_add_f32 v[90:91], v[108:109], v[116:117] op_sel_hi:[1,0] neg_lo:[0,1] neg_hi:[0,1]
	v_pk_add_f32 v[88:89], v[106:107], v[116:117] op_sel_hi:[1,0] neg_lo:[0,1] neg_hi:[0,1]
	v_pk_add_f32 v[82:83], v[100:101], v[82:83]
	v_exp_f32_e32 v88, v88
	v_exp_f32_e32 v90, v90
	v_exp_f32_e32 v91, v91
	v_exp_f32_e32 v89, v89
	v_pk_add_f32 v[82:83], v[92:93], v[82:83]
	v_pk_add_f32 v[102:103], v[86:87], v[102:103]
	v_pk_add_f32 v[82:83], v[94:95], v[82:83]
	v_pk_add_f32 v[102:103], v[90:91], v[102:103]
	v_pk_add_f32 v[82:83], v[84:85], v[82:83]
	s_nop 0
	v_pk_add_f32 v[82:83], v[88:89], v[82:83]
	s_nop 0
	v_add_f32_e32 v82, v82, v83
	v_add_f32_e32 v83, v102, v103
	v_add_f32_e32 v83, v82, v83
	v_mov_b32_e32 v102, v83
	v_sub_f32_e32 v82, v193, v116
	v_exp_f32_e32 v82, v82
	v_permlane16_swap_b32 v83, v102
	v_add_f32_e32 v83, v83, v102
	v_mov_b32_e32 v102, v83
	s_nop 1
	v_permlane32_swap_b32 v83, v102
	v_cmp_neq_f32_e32 vcc, 1.0, v82
	s_cbranch_vccz .LBB0_1727
	v_pk_mul_f32 v[64:65], v[64:65], v[82:83] op_sel_hi:[1,0]
	v_pk_mul_f32 v[62:63], v[62:63], v[82:83] op_sel_hi:[1,0]
	v_pk_mul_f32 v[60:61], v[60:61], v[82:83] op_sel_hi:[1,0]
	v_pk_mul_f32 v[58:59], v[58:59], v[82:83] op_sel_hi:[1,0]
	v_pk_mul_f32 v[56:57], v[56:57], v[82:83] op_sel_hi:[1,0]
	v_pk_mul_f32 v[54:55], v[54:55], v[82:83] op_sel_hi:[1,0]
	v_pk_mul_f32 v[52:53], v[52:53], v[82:83] op_sel_hi:[1,0]
	v_pk_mul_f32 v[50:51], v[50:51], v[82:83] op_sel_hi:[1,0]

; template <int DQK>
; __device__ __forceinline__ void attn_block(const AttnKV& a, const AttnW& gw, char* smem) {
;     ...
;                 const float mnew = fmaxf(m[qt], mx);
;                 const float alpha = __builtin_amdgcn_exp2f(m[qt] - mnew);
;                 m[qt] = mnew;
;                 f32x4 rs4 = {0.f, 0.f, 0.f, 0.f};
;                 const f32x4 negm4 = {-mnew, -mnew, -mnew, -mnew};
; #pragma unroll
;                 for (int nt = 0; nt < 8; ++nt) {
;                     const f32x4 d4 = st[qt][nt] + negm4;
;                     f32x4 e4;
;                     e4[0] = __builtin_amdgcn_exp2f(d4[0]); e4[1] = __builtin_amdgcn_exp2f(d4[1]); e4[2] = __builtin_amdgcn_exp2f(d4[2]); e4[3] = __builtin_amdgcn_exp2f(d4[3]);
;                     st[qt][nt] = e4; rs4 += e4;
;                 }
;                 float rs = (rs4[0] + rs4[1]) + (rs4[2] + rs4[3]);
;                 rs += __shfl_xor(rs, 16); rs += __shfl_xor(rs, 32);
;                 l[qt] = l[qt] * alpha + rs;
.LBB0_1729:
	s_or_b64 exec, exec, s[16:17]
	v_add_f32_e32 v83, v83, v102
	v_fma_f32 v153, v153, v82, v83
	v_add_f32_e32 v115, v115, v117
	v_fma_f32 v192, v192, v114, v115
	s_setprio 0
	v_mov_b32_e32 v186, v168
	v_mov_b32_e32 v193, v116
